# non-temporal hint on the RMSNorm row loads
# speedup vs baseline: 1.0090x; 1.0090x over previous
; __device__ __forceinline__ unsigned cvt_pk_bf16(float lo, float hi) { const f32x2_t v = {lo, hi}; const bf16x2_t b = __builtin_convertvector(v, bf16x2_t); return __builtin_bit_cast(unsigned, b); }
; __device__ void rmsnorm_phase(const float* __restrict__ x, const float* __restrict__ g, bf16_t* h, float* outf) {
;     ...
;     for (int row = gw; row < T_; row += nw) {
;         const float4* xr = (const float4*)(x + (size_t)row * D_);
;         float4 v[4]; float ss = 0.f;
; #pragma unroll
;         for (int i = 0; i < 4; ++i) { v[i] = xr[lane + 64 * i]; ss += v[i].x * v[i].x + v[i].y * v[i].y + v[i].z * v[i].z + v[i].w * v[i].w; }
; #pragma unroll
;         for (int o = 32; o >= 1; o >>= 1) ss += __shfl_xor(ss, o);
;         const float rs = rsqrtf(ss * (1.0f / 1024.0f) + 1e-6f);
; #pragma unroll
;         for (int i = 0; i < 4; ++i) {
;             const float a = v[i].x * rs * gv[i].x, b = v[i].y * rs * gv[i].y, c = v[i].z * rs * gv[i].z, d = v[i].w * rs * gv[i].w;
;             if (outf) ((float4*)(outf + (size_t)row * D_))[lane + 64 * i] = make_float4(a, b, c, d);
;             else { u32x2 w; w.x = cvt_pk_bf16(a, b); w.y = cvt_pk_bf16(c, d); *(u32x2*)(h + (size_t)row * D_ + (lane + 64 * i) * 4) = w; }
;         }
.LBB0_81:
	global_load_dwordx4 v[30:33], v[22:23], off nt
	global_load_dwordx4 v[34:37], v[22:23], off offset:1024 nt
	global_load_dwordx4 v[56:59], v[22:23], off offset:2048 nt
	global_load_dwordx4 v[60:63], v[22:23], off offset:3072 nt
	v_add_u32_e32 v18, s4, v18
	s_waitcnt vmcnt(2)
	v_mov_b32_e32 v44, v31
	v_mov_b32_e32 v45, v35
	v_mov_b32_e32 v42, v30
	v_mov_b32_e32 v43, v34
	v_pk_mul_f32 v[44:45], v[44:45], v[44:45]
	v_mov_b32_e32 v38, v32
	v_mov_b32_e32 v39, v36
	v_pk_fma_f32 v[42:43], v[42:43], v[42:43], v[44:45]
	v_mov_b32_e32 v40, v33
	v_mov_b32_e32 v41, v37
	v_pk_fma_f32 v[38:39], v[38:39], v[38:39], v[42:43]
	s_nop 0
	v_pk_fma_f32 v[46:47], v[40:41], v[40:41], v[38:39]
	v_add_f32_e32 v19, v46, v47
	v_lshl_add_u64 v[22:23], v[22:23], 0, s[8:9]
	s_waitcnt vmcnt(0)
	v_mov_b32_e32 v54, v57
	v_mov_b32_e32 v55, v61
	v_mov_b32_e32 v52, v56
	v_mov_b32_e32 v53, v60
	v_pk_mul_f32 v[54:55], v[54:55], v[54:55]
	v_mov_b32_e32 v48, v58
	v_mov_b32_e32 v49, v62
	v_pk_fma_f32 v[52:53], v[52:53], v[52:53], v[54:55]
	v_mov_b32_e32 v50, v59
	v_mov_b32_e32 v51, v63
	v_pk_fma_f32 v[48:49], v[48:49], v[48:49], v[52:53]
	s_nop 0
	v_pk_fma_f32 v[48:49], v[50:51], v[50:51], v[48:49]
	s_nop 0
	v_add_f32_e32 v19, v19, v48
	v_add_f32_e32 v19, v19, v49
	ds_bpermute_b32 v29, v0, v19
	s_waitcnt lgkmcnt(0)
	v_add_f32_e32 v19, v19, v29
	ds_bpermute_b32 v29, v24, v19
	s_waitcnt lgkmcnt(0)
	v_add_f32_e32 v19, v19, v29
	ds_bpermute_b32 v29, v25, v19
	s_waitcnt lgkmcnt(0)
	v_add_f32_e32 v19, v19, v29
	ds_bpermute_b32 v29, v26, v19
	s_waitcnt lgkmcnt(0)
	v_add_f32_e32 v19, v19, v29
	ds_bpermute_b32 v29, v27, v19
	s_waitcnt lgkmcnt(0)
	v_add_f32_e32 v19, v19, v29
	ds_bpermute_b32 v29, v28, v19
	s_waitcnt lgkmcnt(0)
	v_add_f32_e32 v19, v19, v29
	v_fmamk_f32 v19, v19, 0x3a800000, v169
	v_cmp_gt_f32_e32 vcc, s33, v19
	v_mul_f32_e32 v29, 0x4b800000, v19
	s_nop 0
	v_cndmask_b32_e32 v19, v19, v29, vcc
	v_rsq_f32_e32 v19, v19
	s_nop 0
	v_mul_f32_e32 v29, 0x45800000, v19
	v_cndmask_b32_e32 v46, v19, v29, vcc
	v_pk_mul_f32 v[30:31], v[30:31], v[46:47] op_sel_hi:[1,0]
	v_pk_mul_f32 v[32:33], v[32:33], v[46:47] op_sel_hi:[1,0]
	v_pk_mul_f32 v[30:31], v[2:3], v[30:31]
	v_pk_mul_f32 v[32:33], v[4:5], v[32:33]
	v_cvt_pk_bf16_f32 v30, v30, v31
	v_cvt_pk_bf16_f32 v31, v32, v33
	global_store_dwordx2 v[20:21], v[30:31], off
	v_pk_mul_f32 v[30:31], v[34:35], v[46:47] op_sel_hi:[1,0]
	v_pk_mul_f32 v[32:33], v[36:37], v[46:47] op_sel_hi:[1,0]
	v_pk_mul_f32 v[30:31], v[6:7], v[30:31]
	v_pk_mul_f32 v[32:33], v[8:9], v[32:33]
	v_cvt_pk_bf16_f32 v30, v30, v31
	v_cvt_pk_bf16_f32 v31, v32, v33
	global_store_dwordx2 v[20:21], v[30:31], off offset:512
	v_pk_mul_f32 v[30:31], v[56:57], v[46:47] op_sel_hi:[1,0]
	v_pk_mul_f32 v[32:33], v[58:59], v[46:47] op_sel_hi:[1,0]
	v_pk_mul_f32 v[30:31], v[10:11], v[30:31]
	v_pk_mul_f32 v[32:33], v[12:13], v[32:33]
	v_cvt_pk_bf16_f32 v30, v30, v31
	v_cvt_pk_bf16_f32 v31, v32, v33
	global_store_dwordx2 v[20:21], v[30:31], off offset:1024
	v_pk_mul_f32 v[30:31], v[60:61], v[46:47] op_sel_hi:[1,0]
	v_pk_mul_f32 v[32:33], v[62:63], v[46:47] op_sel_hi:[1,0]
	v_pk_mul_f32 v[30:31], v[14:15], v[30:31]
	v_pk_mul_f32 v[32:33], v[16:17], v[32:33]
	v_cvt_pk_bf16_f32 v30, v30, v31
	v_cvt_pk_bf16_f32 v31, v32, v33
	v_cmp_lt_i32_e32 vcc, s59, v18
	global_store_dwordx2 v[20:21], v[30:31], off offset:1536
	v_lshl_add_u64 v[20:21], v[20:21], 0, s[6:7]
	s_or_b64 s[10:11], vcc, s[10:11]
	s_andn2_b64 exec, exec, s[10:11]
	s_cbranch_execnz .LBB0_81

; __device__ __forceinline__ unsigned cvt_pk_bf16(float lo, float hi) { const f32x2_t v = {lo, hi}; const bf16x2_t b = __builtin_convertvector(v, bf16x2_t); return __builtin_bit_cast(unsigned, b); }
; __device__ void rmsnorm_phase(const float* __restrict__ x, const float* __restrict__ g, bf16_t* h, float* outf) {
;     ...
;     for (int row = gw; row < T_; row += nw) {
;         const float4* xr = (const float4*)(x + (size_t)row * D_);
;         float4 v[4]; float ss = 0.f;
; #pragma unroll
;         for (int i = 0; i < 4; ++i) { v[i] = xr[lane + 64 * i]; ss += v[i].x * v[i].x + v[i].y * v[i].y + v[i].z * v[i].z + v[i].w * v[i].w; }
; #pragma unroll
;         for (int o = 32; o >= 1; o >>= 1) ss += __shfl_xor(ss, o);
;         const float rs = rsqrtf(ss * (1.0f / 1024.0f) + 1e-6f);
; #pragma unroll
;         for (int i = 0; i < 4; ++i) {
;             const float a = v[i].x * rs * gv[i].x, b = v[i].y * rs * gv[i].y, c = v[i].z * rs * gv[i].z, d = v[i].w * rs * gv[i].w;
;             if (outf) ((float4*)(outf + (size_t)row * D_))[lane + 64 * i] = make_float4(a, b, c, d);
;             else { u32x2 w; w.x = cvt_pk_bf16(a, b); w.y = cvt_pk_bf16(c, d); *(u32x2*)(h + (size_t)row * D_ + (lane + 64 * i) * 4) = w; }
;         }
.LBB0_668:
	global_load_dwordx4 v[22:25], v[38:39], off offset:2048 nt
	global_load_dwordx4 v[18:21], v[38:39], off offset:3072 nt
	global_load_dwordx4 v[30:33], v[38:39], off nt
	global_load_dwordx4 v[26:29], v[38:39], off offset:1024 nt
	s_andn2_b64 vcc, exec, s[12:13]
	s_waitcnt vmcnt(0) lgkmcnt(0)
	v_mov_b32_e32 v48, v23
	v_mov_b32_e32 v49, v19
	v_mov_b32_e32 v60, v31
	v_mov_b32_e32 v61, v27
	v_mov_b32_e32 v40, v22
	v_mov_b32_e32 v41, v18
	v_mov_b32_e32 v58, v30
	v_mov_b32_e32 v59, v26
	v_pk_mul_f32 v[48:49], v[48:49], v[48:49]
	v_pk_mul_f32 v[60:61], v[60:61], v[60:61]
	v_mov_b32_e32 v54, v32
	v_mov_b32_e32 v55, v28
	v_pk_fma_f32 v[40:41], v[40:41], v[40:41], v[48:49]
	v_pk_fma_f32 v[48:49], v[58:59], v[58:59], v[60:61]
	v_mov_b32_e32 v50, v24
	v_mov_b32_e32 v51, v20
	v_mov_b32_e32 v56, v33
	v_mov_b32_e32 v57, v29
	v_pk_fma_f32 v[48:49], v[54:55], v[54:55], v[48:49]
	v_mov_b32_e32 v52, v25
	v_mov_b32_e32 v53, v21
	v_pk_fma_f32 v[40:41], v[50:51], v[50:51], v[40:41]
	v_pk_fma_f32 v[48:49], v[56:57], v[56:57], v[48:49]
	v_pk_fma_f32 v[40:41], v[52:53], v[52:53], v[40:41]
	v_add_f32_e32 v35, v48, v49
	v_add_f32_e32 v35, v35, v40
	v_add_f32_e32 v35, v35, v41
	ds_bpermute_b32 v40, v0, v35
	s_waitcnt lgkmcnt(0)
	v_add_f32_e32 v35, v35, v40
	ds_bpermute_b32 v40, v42, v35
	s_waitcnt lgkmcnt(0)
	v_add_f32_e32 v35, v35, v40
	ds_bpermute_b32 v40, v43, v35
	s_waitcnt lgkmcnt(0)
	v_add_f32_e32 v35, v35, v40
	ds_bpermute_b32 v40, v44, v35
	s_waitcnt lgkmcnt(0)
	v_add_f32_e32 v35, v35, v40
	ds_bpermute_b32 v40, v45, v35
	s_waitcnt lgkmcnt(0)
	v_add_f32_e32 v35, v35, v40
	ds_bpermute_b32 v40, v46, v35
	s_waitcnt lgkmcnt(0)
	v_add_f32_e32 v35, v35, v40
	v_fmamk_f32 v35, v35, 0x3a800000, v169
	v_mul_f32_e32 v40, 0x4b800000, v35
	v_cmp_gt_f32_e64 s[4:5], s33, v35
	s_nop 1
	v_cndmask_b32_e64 v35, v35, v40, s[4:5]
	v_rsq_f32_e32 v35, v35
	v_cndmask_b32_e64 v40, 0, 1, s[12:13]
	v_cmp_ne_u32_e64 s[2:3], 1, v40
	v_mul_f32_e32 v40, 0x45800000, v35
	v_cndmask_b32_e64 v40, v35, v40, s[4:5]
	v_pk_mul_f32 v[30:31], v[30:31], v[40:41] op_sel_hi:[1,0]
	v_pk_mul_f32 v[32:33], v[32:33], v[40:41] op_sel_hi:[1,0]
	v_pk_mul_f32 v[30:31], v[2:3], v[30:31]
	v_pk_mul_f32 v[32:33], v[4:5], v[32:33]
	s_cbranch_vccnz .LBB0_679
	global_store_dwordx4 v[38:39], v[30:33], off
	s_cbranch_execnz .LBB0_671

; __device__ __forceinline__ unsigned cvt_pk_bf16(float lo, float hi) { const f32x2_t v = {lo, hi}; const bf16x2_t b = __builtin_convertvector(v, bf16x2_t); return __builtin_bit_cast(unsigned, b); }
; __device__ void rmsnorm_phase(const float* __restrict__ x, const float* __restrict__ g, bf16_t* h, float* outf) {
;     ...
;     for (int row = gw; row < T_; row += nw) {
;         const float4* xr = (const float4*)(x + (size_t)row * D_);
;         float4 v[4]; float ss = 0.f;
; #pragma unroll
;         for (int i = 0; i < 4; ++i) { v[i] = xr[lane + 64 * i]; ss += v[i].x * v[i].x + v[i].y * v[i].y + v[i].z * v[i].z + v[i].w * v[i].w; }
; #pragma unroll
;         for (int o = 32; o >= 1; o >>= 1) ss += __shfl_xor(ss, o);
;         const float rs = rsqrtf(ss * (1.0f / 1024.0f) + 1e-6f);
; #pragma unroll
;         for (int i = 0; i < 4; ++i) {
;             const float a = v[i].x * rs * gv[i].x, b = v[i].y * rs * gv[i].y, c = v[i].z * rs * gv[i].z, d = v[i].w * rs * gv[i].w;
;             if (outf) ((float4*)(outf + (size_t)row * D_))[lane + 64 * i] = make_float4(a, b, c, d);
;             else { u32x2 w; w.x = cvt_pk_bf16(a, b); w.y = cvt_pk_bf16(c, d); *(u32x2*)(h + (size_t)row * D_ + (lane + 64 * i) * 4) = w; }
;         }
.LBB0_942:
	global_load_dwordx4 v[30:33], v[22:23], off nt
	global_load_dwordx4 v[34:37], v[22:23], off offset:1024 nt
	global_load_dwordx4 v[38:41], v[22:23], off offset:2048 nt
	global_load_dwordx4 v[42:45], v[22:23], off offset:3072 nt
	v_add_u32_e32 v18, s4, v18
	v_cmp_lt_i32_e32 vcc, s59, v18
	s_or_b64 s[10:11], vcc, s[10:11]
	v_lshl_add_u64 v[22:23], v[22:23], 0, s[8:9]
	s_waitcnt vmcnt(0) lgkmcnt(0)
	v_mov_b32_e32 v52, v31
	v_mov_b32_e32 v53, v35
	v_mov_b32_e32 v50, v30
	v_mov_b32_e32 v51, v34
	v_mov_b32_e32 v60, v39
	v_mov_b32_e32 v61, v43
	v_pk_mul_f32 v[52:53], v[52:53], v[52:53]
	v_mov_b32_e32 v46, v32
	v_mov_b32_e32 v47, v36
	v_mov_b32_e32 v58, v38
	v_mov_b32_e32 v59, v42
	v_pk_mul_f32 v[60:61], v[60:61], v[60:61]
	v_pk_fma_f32 v[50:51], v[50:51], v[50:51], v[52:53]
	v_mov_b32_e32 v48, v33
	v_mov_b32_e32 v49, v37
	v_mov_b32_e32 v54, v40
	v_mov_b32_e32 v55, v44
	v_pk_fma_f32 v[52:53], v[58:59], v[58:59], v[60:61]
	v_pk_fma_f32 v[46:47], v[46:47], v[46:47], v[50:51]
	v_mov_b32_e32 v56, v41
	v_mov_b32_e32 v57, v45
	v_pk_fma_f32 v[50:51], v[54:55], v[54:55], v[52:53]
	v_pk_fma_f32 v[46:47], v[48:49], v[48:49], v[46:47]
	v_pk_fma_f32 v[48:49], v[56:57], v[56:57], v[50:51]
	v_add_f32_e32 v19, v46, v47
	v_add_f32_e32 v19, v19, v48
	v_add_f32_e32 v19, v19, v49
	ds_bpermute_b32 v29, v0, v19
	s_waitcnt lgkmcnt(0)
	v_add_f32_e32 v19, v19, v29
	ds_bpermute_b32 v29, v24, v19
	s_waitcnt lgkmcnt(0)
	v_add_f32_e32 v19, v19, v29
	ds_bpermute_b32 v29, v25, v19
	s_waitcnt lgkmcnt(0)
	v_add_f32_e32 v19, v19, v29
	ds_bpermute_b32 v29, v26, v19
	s_waitcnt lgkmcnt(0)
	v_add_f32_e32 v19, v19, v29
	ds_bpermute_b32 v29, v27, v19
	s_waitcnt lgkmcnt(0)
	v_add_f32_e32 v19, v19, v29
	ds_bpermute_b32 v29, v28, v19
	s_waitcnt lgkmcnt(0)
	v_add_f32_e32 v19, v19, v29
	v_fmamk_f32 v19, v19, 0x3a800000, v169
	v_mul_f32_e32 v29, 0x4b800000, v19
	v_cmp_gt_f32_e32 vcc, s33, v19
	s_nop 1
	v_cndmask_b32_e32 v19, v19, v29, vcc
	v_rsq_f32_e32 v19, v19
	s_nop 0
	v_mul_f32_e32 v29, 0x45800000, v19
	v_cndmask_b32_e32 v46, v19, v29, vcc
	v_pk_mul_f32 v[30:31], v[30:31], v[46:47] op_sel_hi:[1,0]
	v_pk_mul_f32 v[32:33], v[32:33], v[46:47] op_sel_hi:[1,0]
	v_pk_mul_f32 v[34:35], v[34:35], v[46:47] op_sel_hi:[1,0]
	v_pk_mul_f32 v[36:37], v[36:37], v[46:47] op_sel_hi:[1,0]
	v_pk_mul_f32 v[38:39], v[38:39], v[46:47] op_sel_hi:[1,0]
	v_pk_mul_f32 v[40:41], v[40:41], v[46:47] op_sel_hi:[1,0]
	v_pk_mul_f32 v[42:43], v[42:43], v[46:47] op_sel_hi:[1,0]
	v_pk_mul_f32 v[44:45], v[44:45], v[46:47] op_sel_hi:[1,0]
	v_pk_mul_f32 v[30:31], v[2:3], v[30:31]
	v_pk_mul_f32 v[32:33], v[4:5], v[32:33]
	v_pk_mul_f32 v[34:35], v[6:7], v[34:35]
	v_pk_mul_f32 v[36:37], v[8:9], v[36:37]
	v_pk_mul_f32 v[38:39], v[10:11], v[38:39]
	v_pk_mul_f32 v[40:41], v[12:13], v[40:41]
	v_pk_mul_f32 v[42:43], v[14:15], v[42:43]
	v_pk_mul_f32 v[44:45], v[16:17], v[44:45]
	v_cvt_pk_bf16_f32 v30, v30, v31
	v_cvt_pk_bf16_f32 v31, v32, v33
	v_cvt_pk_bf16_f32 v32, v34, v35
	v_cvt_pk_bf16_f32 v33, v36, v37
	v_cvt_pk_bf16_f32 v34, v38, v39
	v_cvt_pk_bf16_f32 v35, v40, v41
	v_cvt_pk_bf16_f32 v36, v42, v43
	v_cvt_pk_bf16_f32 v37, v44, v45
	global_store_dwordx2 v[20:21], v[30:31], off
	global_store_dwordx2 v[20:21], v[32:33], off offset:512
	global_store_dwordx2 v[20:21], v[34:35], off offset:1024
	global_store_dwordx2 v[20:21], v[36:37], off offset:1536
	v_lshl_add_u64 v[20:21], v[20:21], 0, s[6:7]
	s_andn2_b64 exec, exec, s[10:11]
	s_cbranch_execnz .LBB0_942
